# router normalize: gain/shift/scale vector loads of a token issued with its row loads; hyena load step: 6 row loads + 12 halo loads in flight together, branch-free halo select
# speedup vs baseline: 1.0270x; 1.0037x over previous
; DI float bf2f(u16 v) { return __uint_as_float(((unsigned)v) << 16); }
; DI float lo16(unsigned u) { return __uint_as_float(u << 16); }
; DI float hi16(unsigned u) { return __uint_as_float(u & 0xffff0000u); }
; DI void hyena_lat_item(const P& p, int l, int c, int bp, unsigned char* lds) {
;     ...
;         const u16* zr = ZT + ((size_t)(2 * bp + bq) * 1024 + OFF_HY + k * 256 + c) * L;
;         uint4 v = *(const uint4*)(zr + n0);
;         float x[10];
;         x[0] = n0 > 0 ? bf2f(zr[n0 - 1]) : 0.f;
;         x[9] = n0 + 8 < L ? bf2f(zr[n0 + 8]) : 0.f;
;         x[1] = lo16(v.x); x[2] = hi16(v.x); x[3] = lo16(v.y); x[4] = hi16(v.y); x[5] = lo16(v.z); x[6] = hi16(v.z); x[7] = lo16(v.w); x[8] = hi16(v.w);
; #pragma unroll
;         for (int e = 0; e < 8; ++e) o[k][bq][e] = bs[k] + w[k][0] * x[e] + w[k][1] * x[e + 1] + w[k][2] * x[e + 2];
.LBB0_447:
	v_add_u32_e32 v54, s24, v50
	v_ashrrev_i32_e32 v55, 31, v54
	v_mov_b32_e32 v178, v54
	s_movk_i32 s0, 0x1ff8
	v_cmp_lt_i32_e32 vcc, 0, v54
	v_cmp_gt_i32_e64 s[0:1], s0, v54
	v_lshl_add_u64 v[130:131], v[54:55], 1, s[4:5]
	global_load_dwordx4 v[6:9], v[130:131], off
	global_load_ushort v142, v[130:131], off offset:-2
	global_load_ushort v148, v[130:131], off offset:16
	v_lshl_add_u64 v[132:133], v[54:55], 1, s[10:11]
	global_load_dwordx4 v[30:33], v[132:133], off
	global_load_ushort v143, v[132:133], off offset:-2
	global_load_ushort v149, v[132:133], off offset:16
	v_lshl_add_u64 v[134:135], v[54:55], 1, s[12:13]
	global_load_dwordx4 v[46:49], v[134:135], off
	global_load_ushort v144, v[134:135], off offset:-2
	global_load_ushort v150, v[134:135], off offset:16
	v_lshl_add_u64 v[136:137], v[54:55], 1, s[16:17]
	global_load_dwordx4 v[18:21], v[136:137], off
	global_load_ushort v145, v[136:137], off offset:-2
	global_load_ushort v151, v[136:137], off offset:16
	v_lshl_add_u64 v[138:139], v[54:55], 1, s[18:19]
	global_load_dwordx4 v[2:5], v[138:139], off
	global_load_ushort v146, v[138:139], off offset:-2
	global_load_ushort v152, v[138:139], off offset:16
	v_lshl_add_u64 v[140:141], v[54:55], 1, s[20:21]
	global_load_dwordx4 v[38:41], v[140:141], off
	global_load_ushort v147, v[140:141], off offset:-2
	global_load_ushort v153, v[140:141], off offset:16
	s_waitcnt vmcnt(0)
	v_lshlrev_b32_e32 v142, 16, v142
	v_lshlrev_b32_e32 v148, 16, v148
	v_cndmask_b32_e32 v15, 0, v142, vcc
	v_cndmask_b32_e64 v13, 0, v148, s[0:1]
	v_lshlrev_b32_e32 v143, 16, v143
	v_lshlrev_b32_e32 v149, 16, v149
	v_cndmask_b32_e32 v23, 0, v143, vcc
	v_cndmask_b32_e64 v17, 0, v149, s[0:1]
	v_lshlrev_b32_e32 v144, 16, v144
	v_lshlrev_b32_e32 v150, 16, v150
	v_cndmask_b32_e32 v26, 0, v144, vcc
	v_cndmask_b32_e64 v66, 0, v150, s[0:1]
	v_lshlrev_b32_e32 v145, 16, v145
	v_lshlrev_b32_e32 v151, 16, v151
	v_cndmask_b32_e32 v27, 0, v145, vcc
	v_cndmask_b32_e64 v28, 0, v151, s[0:1]
	v_lshlrev_b32_e32 v146, 16, v146
	v_lshlrev_b32_e32 v152, 16, v152
	v_cndmask_b32_e32 v12, 0, v146, vcc
	v_cndmask_b32_e64 v29, 0, v152, s[0:1]
	v_lshlrev_b32_e32 v147, 16, v147
	v_lshlrev_b32_e32 v153, 16, v153
	v_cndmask_b32_e32 v25, 0, v147, vcc
	v_cndmask_b32_e64 v65, 0, v153, s[0:1]
	s_mov_b64 s[24:25], exec
	s_branch .LBB0_446

; DI unsigned pack2(float a, float b) { fl2_t f = {a, b}; bf2_t r = __builtin_convertvector(f, bf2_t); return __builtin_bit_cast(unsigned, r); }
; DI float wave_sum(float v) { for (int o = 32; o >= 1; o >>= 1) v += shx(v, o); return v; }
; DI size_t boff(int row, int k, int K) { return ((size_t)(row >> 8) * (K >> 6) + (k >> 6)) * 16384 + (row & 255) * 64 + (k & 63); }
; DI void router_phase(const P& p, int l, int ntok, unsigned char* lds) {
;     ...
;       int tl = w * 4 + q;
;       int tok = tbase + c0 + tl;
;       bool valid = (c0 + tl) < per;
;       if (!valid) tok = tbase;
;       const float* xr = XA + (size_t)tok * D;
;       int mr = tok < T ? (tok >> 13) : 4;
;       float xv[16];
; #pragma unroll
;       for (int i = 0; i < 4; ++i) { float4 v = *(const float4*)(xr + (i * 64 + lane) * 4); xv[4 * i] = v.x; xv[4 * i + 1] = v.y; xv[4 * i + 2] = v.z; xv[4 * i + 3] = v.w; }
;       float ss = 0.f;
; #pragma unroll
;       for (int i = 0; i < 16; ++i) ss += xv[i] * xv[i];
;       ss = wave_sum(ss);
;       float rinv = rsqrtf(ss * (1.f / 1024.f) + 1e-6f);
;       const float* g = p.in[I_N2G] + l * 1024; const float* sh = MOD + mr * 6144 + 3 * 1024; const float* sc = MOD + mr * 6144 + 4 * 1024;
; #pragma unroll
;       for (int i = 0; i < 4; ++i) {
;         int c = (i * 64 + lane) * 4;
;         float4 gv = *(const float4*)(g + c), shv = *(const float4*)(sh + c), scv = *(const float4*)(sc + c);
;         float h0 = xv[4 * i] * rinv * gv.x * (1.f + scv.x) + shv.x;
;         float h1 = xv[4 * i + 1] * rinv * gv.y * (1.f + scv.y) + shv.y;
;         float h2 = xv[4 * i + 2] * rinv * gv.z * (1.f + scv.z) + shv.z;
;         float h3 = xv[4 * i + 3] * rinv * gv.w * (1.f + scv.w) + shv.w;
;         float* tr = tile + tl * 1025 + c;
;         tr[0] = h0; tr[1] = h1; tr[2] = h2; tr[3] = h3;
;         if (valid) *(uint2*)(H + boff(tok, c, 1024)) = make_uint2(pack2(h0, h1), pack2(h2, h3));
.LBB0_1242:
	v_add_u32_e32 v64, s17, v39
	v_add_u32_e32 v65, s17, v71
	v_cmp_gt_i32_e32 vcc, s21, v64
	v_mov_b32_e32 v2, s19
	v_add_u32_e32 v66, s16, v70
	v_cndmask_b32_e32 v2, v2, v65, vcc
	v_min_i32_e32 v16, 0x8000, v2
	v_ashrrev_i32_e32 v16, 13, v16
	v_mul_i32_i24_e32 v16, 0x1800, v16
	v_ashrrev_i32_e32 v17, 31, v16
	v_lshl_add_u64 v[16:17], v[16:17], 2, s[96:97]
	v_lshl_add_u64 v[58:59], v[16:17], 0, s[88:89]
	v_lshl_add_u64 v[60:61], v[16:17], 0, s[74:75]
	v_ashrrev_i32_e32 v16, 8, v65
	v_ashrrev_i32_e32 v17, 31, v16
	v_ashrrev_i32_e32 v3, 31, v2
	v_and_b32_e32 v18, 0x3fc0, v66
	v_lshlrev_b64 v[16:17], 19, v[16:17]
	v_lshlrev_b64 v[4:5], 12, v[2:3]
	v_lshl_add_u64 v[16:17], s[44:45], 0, v[16:17]
	v_lshlrev_b32_e32 v178, 1, v18
	v_lshl_add_u64 v[14:15], v[48:49], 0, v[4:5]
	v_lshl_add_u64 v[16:17], v[16:17], 0, v[178:179]
	v_mov_b32_e32 v53, v179
	global_load_dwordx4 v[10:13], v[14:15], off offset:1024
	global_load_dwordx4 v[6:9], v[14:15], off offset:2048
	global_load_dwordx4 v[2:5], v[14:15], off offset:3072
	v_lshl_add_u64 v[56:57], v[16:17], 0, v[52:53]
	global_load_dwordx4 v[14:17], v[14:15], off
	v_mov_b32_e32 v55, v179
	v_lshl_add_u64 v[18:19], v[58:59], 0, v[54:55]
	v_lshl_add_u64 v[26:27], v[60:61], 0, v[54:55]
	v_lshl_add_u64 v[206:207], v[58:59], 0, v[54:55]
	v_lshl_add_u64 v[208:209], v[60:61], 0, v[54:55]
	global_load_dwordx4 v[130:133], v[46:47], off
	global_load_dwordx4 v[146:149], v[206:207], off
	global_load_dwordx4 v[184:187], v[208:209], off
	global_load_dwordx4 v[134:137], v[46:47], off offset:1024
	global_load_dwordx4 v[152:155], v[206:207], off offset:1024
	global_load_dwordx4 v[194:197], v[208:209], off offset:1024
	global_load_dwordx4 v[138:141], v[46:47], off offset:2048
	global_load_dwordx4 v[156:159], v[206:207], off offset:2048
	global_load_dwordx4 v[198:201], v[208:209], off offset:2048
	global_load_dwordx4 v[142:145], v[46:47], off offset:3072
	global_load_dwordx4 v[180:183], v[206:207], off offset:3072
	global_load_dwordx4 v[202:205], v[208:209], off offset:3072
	s_waitcnt vmcnt(0)
	v_pk_mul_f32 v[20:21], v[10:11], v[10:11]
	v_pk_mul_f32 v[22:23], v[12:13], v[12:13]
	v_pk_mul_f32 v[24:25], v[6:7], v[6:7]
	v_pk_mul_f32 v[28:29], v[8:9], v[8:9]
	v_pk_mul_f32 v[80:81], v[14:15], v[14:15]
	v_pk_mul_f32 v[78:79], v[16:17], v[16:17]
	v_add_f32_e32 v53, v80, v81
	v_add_f32_e32 v53, v53, v78
	v_add_f32_e32 v53, v53, v79
	v_add_f32_e32 v20, v53, v20
	v_add_f32_e32 v20, v20, v21
	v_add_f32_e32 v20, v20, v22
	v_add_f32_e32 v20, v20, v23
	v_add_f32_e32 v20, v20, v24
	v_add_f32_e32 v20, v20, v25
	v_add_f32_e32 v20, v20, v28
	v_pk_mul_f32 v[62:63], v[2:3], v[2:3]
	v_add_f32_e32 v20, v20, v29
	v_add_f32_e32 v20, v20, v62
	v_mov_b32_e32 v21, v215
	v_pk_mul_f32 v[76:77], v[4:5], v[4:5]
	v_add_f32_e32 v20, v20, v63
	v_add_f32_e32 v20, v20, v76
	v_lshlrev_b32_e32 v21, 2, v21
	v_add_f32_e32 v20, v20, v77
	v_bitop3_b32 v21, v21, s76, v220 bitop3:0x6c
	ds_bpermute_b32 v21, v21, v20
	s_waitcnt lgkmcnt(0)
	v_add_f32_e32 v20, v20, v21
	v_mov_b32_e32 v21, v215
	s_nop 0
	v_lshlrev_b32_e32 v21, 2, v21
	v_bitop3_b32 v21, v21, 64, v220 bitop3:0x6c
	ds_bpermute_b32 v21, v21, v20
	s_waitcnt lgkmcnt(0)
	v_add_f32_e32 v20, v20, v21
	v_mov_b32_e32 v21, v215
	s_nop 0
	v_lshlrev_b32_e32 v21, 2, v21
	v_bitop3_b32 v21, v21, 32, v220 bitop3:0x6c
	ds_bpermute_b32 v21, v21, v20
	s_waitcnt lgkmcnt(0)
	v_add_f32_e32 v20, v20, v21
	v_mov_b32_e32 v21, v215
	s_nop 0
	v_lshlrev_b32_e32 v21, 2, v21
	v_bitop3_b32 v21, v21, 16, v220 bitop3:0x6c
	ds_bpermute_b32 v21, v21, v20
	s_waitcnt lgkmcnt(0)
	v_add_f32_e32 v20, v20, v21
	v_mov_b32_e32 v21, v215
	s_nop 0
	v_lshlrev_b32_e32 v21, 2, v21
	v_bitop3_b32 v21, v21, 8, v220 bitop3:0x6c
	ds_bpermute_b32 v21, v21, v20
	s_waitcnt lgkmcnt(0)
	v_add_f32_e32 v20, v20, v21
	v_mov_b32_e32 v21, v215
	s_nop 0
	v_lshlrev_b32_e32 v21, 2, v21
	v_bitop3_b32 v21, v21, 4, v220 bitop3:0x6c
	ds_bpermute_b32 v21, v21, v20
	s_waitcnt lgkmcnt(0)
	v_add_f32_e32 v20, v20, v21
	v_fmamk_f32 v20, v20, 0x3a800000, v212
	v_cmp_gt_f32_e64 s[0:1], s77, v20
	v_mul_f32_e32 v21, 0x4b800000, v20
	s_nop 0
	v_cndmask_b32_e64 v20, v20, v21, s[0:1]
	v_rsq_f32_e32 v20, v20
	s_nop 0
	v_mul_f32_e32 v21, 0x45800000, v20
	v_cndmask_b32_e64 v62, v20, v21, s[0:1]
	v_mov_b64_e32 v[22:23], v[130:131]
	v_mov_b64_e32 v[24:25], v[132:133]
	s_nop 0
	v_mov_b64_e32 v[18:19], v[146:147]
	v_mov_b64_e32 v[20:21], v[148:149]
	s_nop 0
	v_mov_b64_e32 v[26:27], v[184:185]
	v_mov_b64_e32 v[28:29], v[186:187]
	v_pk_mul_f32 v[14:15], v[14:15], v[62:63] op_sel_hi:[1,0]
	v_pk_mul_f32 v[16:17], v[16:17], v[62:63] op_sel_hi:[1,0]
	s_waitcnt vmcnt(2)
	v_pk_mul_f32 v[14:15], v[22:23], v[14:15]
	v_pk_mul_f32 v[16:17], v[24:25], v[16:17]
	s_waitcnt vmcnt(0)
	v_pk_add_f32 v[22:23], v[26:27], 1.0 op_sel_hi:[1,0]
	v_lshlrev_b32_e32 v24, 1, v38
	v_pk_fma_f32 v[14:15], v[22:23], v[14:15], v[18:19]
	v_pk_add_f32 v[18:19], v[28:29], 1.0 op_sel_hi:[1,0]
	s_nop 0
	v_pk_fma_f32 v[16:17], v[16:17], v[18:19], v[20:21]
	ds_write2_b64 v75, v[14:15], v[16:17] offset1:1
	s_and_saveexec_b64 s[0:1], vcc
	s_cbranch_execz .LBB0_1244
	v_mov_b32_e32 v25, v179
	v_cvt_pk_bf16_f32 v14, v14, v15
	v_cvt_pk_bf16_f32 v15, v16, v17
	v_lshl_add_u64 v[16:17], v[56:57], 0, v[24:25]
	global_store_dwordx2 v[16:17], v[14:15], off
; DI unsigned pack2(float a, float b) { fl2_t f = {a, b}; bf2_t r = __builtin_convertvector(f, bf2_t); return __builtin_bit_cast(unsigned, r); }
; DI size_t boff(int row, int k, int K) { return ((size_t)(row >> 8) * (K >> 6) + (k >> 6)) * 16384 + (row & 255) * 64 + (k & 63); }
; DI void router_phase(const P& p, int l, int ntok, unsigned char* lds) {
;     ...
;       const float* xr = XA + (size_t)tok * D;
;       int mr = tok < T ? (tok >> 13) : 4;
;       float xv[16];
; #pragma unroll
;       for (int i = 0; i < 4; ++i) { float4 v = *(const float4*)(xr + (i * 64 + lane) * 4); xv[4 * i] = v.x; xv[4 * i + 1] = v.y; xv[4 * i + 2] = v.z; xv[4 * i + 3] = v.w; }
;     ...
;       for (int i = 0; i < 4; ++i) {
;         int c = (i * 64 + lane) * 4;
;         float4 gv = *(const float4*)(g + c), shv = *(const float4*)(sh + c), scv = *(const float4*)(sc + c);
;         float h0 = xv[4 * i] * rinv * gv.x * (1.f + scv.x) + shv.x;
;         float h1 = xv[4 * i + 1] * rinv * gv.y * (1.f + scv.y) + shv.y;
;         float h2 = xv[4 * i + 2] * rinv * gv.z * (1.f + scv.z) + shv.z;
;         float h3 = xv[4 * i + 3] * rinv * gv.w * (1.f + scv.w) + shv.w;
;         float* tr = tile + tl * 1025 + c;
;         tr[0] = h0; tr[1] = h1; tr[2] = h2; tr[3] = h3;
;         if (valid) *(uint2*)(H + boff(tok, c, 1024)) = make_uint2(pack2(h0, h1), pack2(h2, h3));
.LBB0_1244:
	s_or_b64 exec, exec, s[0:1]
	v_lshlrev_b32_e32 v178, 2, v32
	v_lshl_add_u64 v[18:19], v[60:61], 0, v[178:179]
	v_mov_b64_e32 v[14:15], v[134:135]
	v_mov_b64_e32 v[16:17], v[136:137]
	v_lshl_add_u64 v[22:23], v[58:59], 0, v[178:179]
	v_mov_b64_e32 v[18:19], v[194:195]
	v_mov_b64_e32 v[20:21], v[196:197]
	v_mov_b32_e32 v63, v62
	v_mov_b64_e32 v[26:27], v[152:153]
	v_mov_b64_e32 v[28:29], v[154:155]
	v_pk_mul_f32 v[10:11], v[10:11], v[62:63]
	v_pk_mul_f32 v[12:13], v[12:13], v[62:63]
	s_waitcnt vmcnt(2)
	v_pk_mul_f32 v[10:11], v[10:11], v[14:15]
	v_pk_mul_f32 v[12:13], v[12:13], v[16:17]
	s_waitcnt vmcnt(1)
	v_pk_add_f32 v[14:15], v[18:19], 1.0 op_sel_hi:[1,0]
	v_pk_add_f32 v[16:17], v[20:21], 1.0 op_sel_hi:[1,0]
	s_waitcnt vmcnt(0)
	v_pk_fma_f32 v[10:11], v[10:11], v[14:15], v[26:27]
	v_pk_fma_f32 v[12:13], v[12:13], v[16:17], v[28:29]
	v_lshlrev_b32_e32 v20, 1, v40
	ds_write2_b64 v75, v[10:11], v[12:13] offset0:128 offset1:129
	s_and_saveexec_b64 s[0:1], vcc
	s_cbranch_execz .LBB0_1246
	v_mov_b32_e32 v21, v179
	v_cvt_pk_bf16_f32 v10, v10, v11
	v_cvt_pk_bf16_f32 v11, v12, v13
	v_lshl_add_u64 v[12:13], v[56:57], 0, v[20:21]
	global_store_dwordx2 v[12:13], v[10:11], off
.LBB0_1246:
	s_or_b64 exec, exec, s[0:1]
	v_lshlrev_b32_e32 v18, 2, v34
	v_mov_b32_e32 v19, v179
	v_lshl_add_u64 v[14:15], v[60:61], 0, v[18:19]
	v_mov_b64_e32 v[10:11], v[138:139]
	v_mov_b64_e32 v[12:13], v[140:141]
	v_lshl_add_u64 v[22:23], v[58:59], 0, v[18:19]
	v_mov_b64_e32 v[14:15], v[198:199]
	v_mov_b64_e32 v[16:17], v[200:201]
	v_pk_mul_f32 v[6:7], v[6:7], v[62:63]
	v_mov_b64_e32 v[26:27], v[156:157]
	v_mov_b64_e32 v[28:29], v[158:159]
	v_pk_mul_f32 v[8:9], v[8:9], v[62:63]
	v_add_u32_e32 v19, 0x800, v75
	s_waitcnt vmcnt(2)
	v_pk_mul_f32 v[6:7], v[6:7], v[10:11]
	v_pk_mul_f32 v[8:9], v[8:9], v[12:13]
	s_waitcnt vmcnt(1)
	v_pk_add_f32 v[10:11], v[14:15], 1.0 op_sel_hi:[1,0]
	v_pk_add_f32 v[12:13], v[16:17], 1.0 op_sel_hi:[1,0]
	s_waitcnt vmcnt(0)
	v_pk_fma_f32 v[6:7], v[6:7], v[10:11], v[26:27]
	v_pk_fma_f32 v[8:9], v[8:9], v[12:13], v[28:29]
	v_lshlrev_b32_e32 v26, 1, v42
	ds_write2_b64 v19, v[6:7], v[8:9] offset1:1
	s_and_saveexec_b64 s[0:1], vcc
	s_cbranch_execz .LBB0_1248
	v_mov_b32_e32 v27, v179
	v_cvt_pk_bf16_f32 v6, v6, v7
	v_cvt_pk_bf16_f32 v7, v8, v9
	v_lshl_add_u64 v[8:9], v[56:57], 0, v[26:27]
	global_store_dwordx2 v[8:9], v[6:7], off
.LBB0_1248:
	s_or_b64 exec, exec, s[0:1]
	v_lshlrev_b32_e32 v22, 2, v36
	v_mov_b32_e32 v23, v179
	v_lshl_add_u64 v[10:11], v[60:61], 0, v[22:23]
	v_mov_b64_e32 v[6:7], v[142:143]
	v_mov_b64_e32 v[8:9], v[144:145]
	v_lshl_add_u64 v[14:15], v[58:59], 0, v[22:23]
	v_mov_b64_e32 v[10:11], v[202:203]
	v_mov_b64_e32 v[12:13], v[204:205]
	v_pk_mul_f32 v[2:3], v[2:3], v[62:63]
	v_mov_b64_e32 v[14:15], v[180:181]
	v_mov_b64_e32 v[16:17], v[182:183]
	v_pk_mul_f32 v[4:5], v[4:5], v[62:63]
	v_add_u32_e32 v19, 0xc00, v75
	v_lshlrev_b32_e32 v28, 1, v44
	s_waitcnt vmcnt(2)
	v_pk_mul_f32 v[2:3], v[2:3], v[6:7]
	v_pk_mul_f32 v[4:5], v[4:5], v[8:9]
	s_waitcnt vmcnt(1)
	v_pk_add_f32 v[6:7], v[10:11], 1.0 op_sel_hi:[1,0]
	v_pk_add_f32 v[8:9], v[12:13], 1.0 op_sel_hi:[1,0]
	s_waitcnt vmcnt(0)
	v_pk_fma_f32 v[2:3], v[2:3], v[6:7], v[14:15]
	v_pk_fma_f32 v[4:5], v[4:5], v[8:9], v[16:17]
	ds_write2_b64 v19, v[2:3], v[4:5] offset1:1
	s_and_saveexec_b64 s[0:1], vcc
	s_cbranch_execz .LBB0_1250
	v_mov_b32_e32 v29, v179
	v_cvt_pk_bf16_f32 v2, v2, v3
	v_cvt_pk_bf16_f32 v3, v4, v5
	v_lshl_add_u64 v[4:5], v[56:57], 0, v[28:29]
	global_store_dwordx2 v[4:5], v[2:3], off
.LBB0_1250:
	s_or_b64 exec, exec, s[0:1]
	v_add_u32_e32 v2, 1, v64
	v_add_u32_e32 v19, 1, v65
	v_cmp_gt_i32_e32 vcc, s21, v2
	v_mov_b32_e32 v2, s19
	v_mov_b32_e32 v57, v179
	v_cndmask_b32_e32 v2, v2, v19, vcc
	v_min_i32_e32 v16, 0x8000, v2
	v_ashrrev_i32_e32 v16, 13, v16
	v_mul_i32_i24_e32 v16, 0x1800, v16
	v_ashrrev_i32_e32 v17, 31, v16
	v_lshl_add_u64 v[16:17], v[16:17], 2, s[96:97]
	v_lshl_add_u64 v[58:59], v[16:17], 0, s[88:89]
	v_lshl_add_u64 v[60:61], v[16:17], 0, s[74:75]
	v_ashrrev_i32_e32 v16, 8, v19
	v_ashrrev_i32_e32 v17, 31, v16
	v_add_u32_e32 v19, 64, v66
	v_ashrrev_i32_e32 v3, 31, v2
	v_and_b32_e32 v19, 0x3fc0, v19
	v_lshlrev_b64 v[16:17], 19, v[16:17]
	v_lshlrev_b64 v[4:5], 12, v[2:3]
	v_lshl_add_u64 v[16:17], s[44:45], 0, v[16:17]
	v_lshlrev_b32_e32 v56, 1, v19
	v_lshl_add_u64 v[14:15], v[48:49], 0, v[4:5]
	v_lshl_add_u64 v[16:17], v[16:17], 0, v[56:57]
	v_mov_b32_e32 v53, v179
	global_load_dwordx4 v[10:13], v[14:15], off offset:1024
	global_load_dwordx4 v[6:9], v[14:15], off offset:2048
	global_load_dwordx4 v[2:5], v[14:15], off offset:3072
	v_lshl_add_u64 v[56:57], v[16:17], 0, v[52:53]
	global_load_dwordx4 v[14:17], v[14:15], off
	v_mov_b32_e32 v21, v215
	v_mov_b32_e32 v55, v179
	v_lshlrev_b32_e32 v21, 2, v21
	v_bitop3_b32 v21, v21, s76, v220 bitop3:0x6c
	v_lshl_add_u64 v[66:67], v[58:59], 0, v[54:55]
	v_lshl_add_u64 v[64:65], v[60:61], 0, v[54:55]
	v_lshl_add_u64 v[206:207], v[58:59], 0, v[54:55]
	v_lshl_add_u64 v[208:209], v[60:61], 0, v[54:55]
	global_load_dwordx4 v[130:133], v[46:47], off
	global_load_dwordx4 v[146:149], v[206:207], off
	global_load_dwordx4 v[184:187], v[208:209], off
	global_load_dwordx4 v[134:137], v[46:47], off offset:1024
	global_load_dwordx4 v[152:155], v[206:207], off offset:1024
	global_load_dwordx4 v[194:197], v[208:209], off offset:1024
	global_load_dwordx4 v[138:141], v[46:47], off offset:2048
	global_load_dwordx4 v[156:159], v[206:207], off offset:2048
	global_load_dwordx4 v[198:201], v[208:209], off offset:2048
	global_load_dwordx4 v[142:145], v[46:47], off offset:3072
	global_load_dwordx4 v[180:183], v[206:207], off offset:3072
	global_load_dwordx4 v[202:205], v[208:209], off offset:3072
	s_waitcnt vmcnt(3)
; DI unsigned pack2(float a, float b) { fl2_t f = {a, b}; bf2_t r = __builtin_convertvector(f, bf2_t); return __builtin_bit_cast(unsigned, r); }
; DI float wave_sum(float v) { for (int o = 32; o >= 1; o >>= 1) v += shx(v, o); return v; }
; DI size_t boff(int row, int k, int K) { return ((size_t)(row >> 8) * (K >> 6) + (k >> 6)) * 16384 + (row & 255) * 64 + (k & 63); }
; DI void router_phase(const P& p, int l, int ntok, unsigned char* lds) {
;     ...
;       float ss = 0.f;
; #pragma unroll
;       for (int i = 0; i < 16; ++i) ss += xv[i] * xv[i];
;       ss = wave_sum(ss);
;       float rinv = rsqrtf(ss * (1.f / 1024.f) + 1e-6f);
;       const float* g = p.in[I_N2G] + l * 1024; const float* sh = MOD + mr * 6144 + 3 * 1024; const float* sc = MOD + mr * 6144 + 4 * 1024;
; #pragma unroll
;       for (int i = 0; i < 4; ++i) {
;         int c = (i * 64 + lane) * 4;
;         float4 gv = *(const float4*)(g + c), shv = *(const float4*)(sh + c), scv = *(const float4*)(sc + c);
;         float h0 = xv[4 * i] * rinv * gv.x * (1.f + scv.x) + shv.x;
;         float h1 = xv[4 * i + 1] * rinv * gv.y * (1.f + scv.y) + shv.y;
;         float h2 = xv[4 * i + 2] * rinv * gv.z * (1.f + scv.z) + shv.z;
;         float h3 = xv[4 * i + 3] * rinv * gv.w * (1.f + scv.w) + shv.w;
;         float* tr = tile + tl * 1025 + c;
;         tr[0] = h0; tr[1] = h1; tr[2] = h2; tr[3] = h3;
;         if (valid) *(uint2*)(H + boff(tok, c, 1024)) = make_uint2(pack2(h0, h1), pack2(h2, h3));
	v_pk_mul_f32 v[62:63], v[10:11], v[10:11]
	v_pk_mul_f32 v[76:77], v[12:13], v[12:13]
	s_waitcnt vmcnt(2)
	v_pk_mul_f32 v[78:79], v[6:7], v[6:7]
	v_pk_mul_f32 v[80:81], v[8:9], v[8:9]
	s_waitcnt vmcnt(0)
	v_pk_mul_f32 v[88:89], v[14:15], v[14:15]
	v_pk_mul_f32 v[86:87], v[16:17], v[16:17]
	v_add_f32_e32 v19, v88, v89
	v_add_f32_e32 v19, v19, v86
	v_add_f32_e32 v19, v19, v87
	v_add_f32_e32 v19, v19, v62
	v_add_f32_e32 v19, v19, v63
	v_add_f32_e32 v19, v19, v76
	v_add_f32_e32 v19, v19, v77
	v_add_f32_e32 v19, v19, v78
	v_add_f32_e32 v19, v19, v79
	v_add_f32_e32 v19, v19, v80
	v_pk_mul_f32 v[82:83], v[2:3], v[2:3]
	v_add_f32_e32 v19, v19, v81
	v_add_f32_e32 v19, v19, v82
	v_pk_mul_f32 v[84:85], v[4:5], v[4:5]
	v_add_f32_e32 v19, v19, v83
	v_add_f32_e32 v19, v19, v84
	v_add_f32_e32 v19, v19, v85
	ds_bpermute_b32 v21, v21, v19
	s_waitcnt lgkmcnt(0)
	v_add_f32_e32 v19, v19, v21
	v_mov_b32_e32 v21, v215
	s_nop 0
	v_lshlrev_b32_e32 v21, 2, v21
	v_bitop3_b32 v21, v21, 64, v220 bitop3:0x6c
	ds_bpermute_b32 v21, v21, v19
	s_waitcnt lgkmcnt(0)
	v_add_f32_e32 v19, v19, v21
	v_mov_b32_e32 v21, v215
	s_nop 0
	v_lshlrev_b32_e32 v21, 2, v21
	v_bitop3_b32 v21, v21, 32, v220 bitop3:0x6c
	ds_bpermute_b32 v21, v21, v19
	s_waitcnt lgkmcnt(0)
	v_add_f32_e32 v19, v19, v21
	v_mov_b32_e32 v21, v215
	s_nop 0
	v_lshlrev_b32_e32 v21, 2, v21
	v_bitop3_b32 v21, v21, 16, v220 bitop3:0x6c
	ds_bpermute_b32 v21, v21, v19
	s_waitcnt lgkmcnt(0)
	v_add_f32_e32 v19, v19, v21
	v_mov_b32_e32 v21, v215
	s_nop 0
	v_lshlrev_b32_e32 v21, 2, v21
	v_bitop3_b32 v21, v21, 8, v220 bitop3:0x6c
	ds_bpermute_b32 v21, v21, v19
	s_waitcnt lgkmcnt(0)
	v_add_f32_e32 v19, v19, v21
	v_mov_b32_e32 v21, v215
	v_mov_b64_e32 v[76:77], v[130:131]
	v_mov_b64_e32 v[78:79], v[132:133]
	v_mov_b64_e32 v[80:81], v[146:147]
	v_mov_b64_e32 v[82:83], v[148:149]
	s_nop 0
	v_mov_b64_e32 v[64:65], v[184:185]
	v_mov_b64_e32 v[66:67], v[186:187]
	v_lshlrev_b32_e32 v21, 2, v21
	v_bitop3_b32 v21, v21, 4, v220 bitop3:0x6c
	ds_bpermute_b32 v21, v21, v19
	s_waitcnt lgkmcnt(0)
	v_add_f32_e32 v19, v19, v21
	v_fmamk_f32 v19, v19, 0x3a800000, v212
	v_cmp_gt_f32_e64 s[0:1], s77, v19
	v_mul_f32_e32 v21, 0x4b800000, v19
	s_waitcnt vmcnt(0)
	v_pk_add_f32 v[64:65], v[64:65], 1.0 op_sel_hi:[1,0]
	v_cndmask_b32_e64 v19, v19, v21, s[0:1]
	v_rsq_f32_e32 v19, v19
	s_nop 0
	v_mul_f32_e32 v21, 0x45800000, v19
	v_cndmask_b32_e64 v62, v19, v21, s[0:1]
	v_pk_mul_f32 v[14:15], v[14:15], v[62:63] op_sel_hi:[1,0]
	v_pk_mul_f32 v[16:17], v[16:17], v[62:63] op_sel_hi:[1,0]
	v_pk_mul_f32 v[14:15], v[76:77], v[14:15]
	v_pk_mul_f32 v[16:17], v[78:79], v[16:17]
	v_pk_fma_f32 v[14:15], v[64:65], v[14:15], v[80:81]
	v_pk_add_f32 v[64:65], v[66:67], 1.0 op_sel_hi:[1,0]
	v_add_u32_e32 v19, 0x1004, v75
	v_pk_fma_f32 v[16:17], v[16:17], v[64:65], v[82:83]
	ds_write2_b32 v19, v14, v15 offset1:1
	v_add_u32_e32 v19, 0x100c, v75
	ds_write2_b32 v19, v16, v17 offset1:1
	s_and_saveexec_b64 s[0:1], vcc
	s_cbranch_execz .LBB0_1252
	v_mov_b32_e32 v25, v179
	v_cvt_pk_bf16_f32 v14, v14, v15
	v_cvt_pk_bf16_f32 v15, v16, v17
	v_lshl_add_u64 v[16:17], v[56:57], 0, v[24:25]
	global_store_dwordx2 v[16:17], v[14:15], off
.LBB0_1252:
	s_or_b64 exec, exec, s[0:1]
	v_lshl_add_u64 v[24:25], v[60:61], 0, v[178:179]
	v_mov_b64_e32 v[14:15], v[134:135]
	v_mov_b64_e32 v[16:17], v[136:137]
	v_mov_b64_e32 v[64:65], v[194:195]
	v_mov_b64_e32 v[66:67], v[196:197]
	v_lshl_add_u64 v[24:25], v[58:59], 0, v[178:179]
	v_mov_b64_e32 v[76:77], v[152:153]
	v_mov_b64_e32 v[78:79], v[154:155]
	v_mov_b32_e32 v63, v62
	v_pk_mul_f32 v[10:11], v[10:11], v[62:63]
	v_pk_mul_f32 v[12:13], v[12:13], v[62:63]
	v_add_u32_e32 v19, 0x1404, v75
	v_add_u32_e32 v21, 0x140c, v75
	s_waitcnt vmcnt(2)
	v_pk_mul_f32 v[10:11], v[10:11], v[14:15]
	v_pk_mul_f32 v[12:13], v[12:13], v[16:17]
	s_waitcnt vmcnt(1)
	v_pk_add_f32 v[14:15], v[64:65], 1.0 op_sel_hi:[1,0]
	v_pk_add_f32 v[16:17], v[66:67], 1.0 op_sel_hi:[1,0]
	s_waitcnt vmcnt(0)
	v_pk_fma_f32 v[10:11], v[10:11], v[14:15], v[76:77]
	v_pk_fma_f32 v[12:13], v[12:13], v[16:17], v[78:79]
	ds_write2_b32 v19, v10, v11 offset1:1
	ds_write2_b32 v21, v12, v13 offset1:1
	s_and_saveexec_b64 s[0:1], vcc
	s_cbranch_execz .LBB0_1254
	v_mov_b32_e32 v21, v179
	v_cvt_pk_bf16_f32 v10, v10, v11
	v_cvt_pk_bf16_f32 v11, v12, v13
	v_lshl_add_u64 v[12:13], v[56:57], 0, v[20:21]
	global_store_dwordx2 v[12:13], v[10:11], off
.LBB0_1254:
	s_or_b64 exec, exec, s[0:1]
	v_mov_b32_e32 v19, v179
	v_lshl_add_u64 v[14:15], v[60:61], 0, v[18:19]
	v_mov_b64_e32 v[10:11], v[138:139]
	v_mov_b64_e32 v[12:13], v[140:141]
	v_lshl_add_u64 v[18:19], v[58:59], 0, v[18:19]
	v_mov_b64_e32 v[14:15], v[198:199]
	v_mov_b64_e32 v[16:17], v[200:201]
	v_pk_mul_f32 v[6:7], v[6:7], v[62:63]
	v_mov_b64_e32 v[18:19], v[156:157]
	v_mov_b64_e32 v[20:21], v[158:159]
	v_pk_mul_f32 v[8:9], v[8:9], v[62:63]
	v_add_u32_e32 v23, 0x1804, v75
	v_add_u32_e32 v24, 0x180c, v75
	s_waitcnt vmcnt(2)
	v_pk_mul_f32 v[6:7], v[6:7], v[10:11]
	v_pk_mul_f32 v[8:9], v[8:9], v[12:13]
	s_waitcnt vmcnt(1)
	v_pk_add_f32 v[10:11], v[14:15], 1.0 op_sel_hi:[1,0]
	v_pk_add_f32 v[12:13], v[16:17], 1.0 op_sel_hi:[1,0]
	s_waitcnt vmcnt(0)
	v_pk_fma_f32 v[6:7], v[6:7], v[10:11], v[18:19]
	v_pk_fma_f32 v[8:9], v[8:9], v[12:13], v[20:21]
	ds_write2_b32 v23, v6, v7 offset1:1
	ds_write2_b32 v24, v8, v9 offset1:1
	s_and_saveexec_b64 s[0:1], vcc
	s_cbranch_execz .LBB0_1256
	v_mov_b32_e32 v27, v179
	v_cvt_pk_bf16_f32 v6, v6, v7
	v_cvt_pk_bf16_f32 v7, v8, v9
	v_lshl_add_u64 v[8:9], v[56:57], 0, v[26:27]
	global_store_dwordx2 v[8:9], v[6:7], off
.LBB0_1256:
	s_or_b64 exec, exec, s[0:1]
	v_mov_b32_e32 v23, v179
	v_lshl_add_u64 v[10:11], v[60:61], 0, v[22:23]
	v_mov_b64_e32 v[6:7], v[142:143]
	v_mov_b64_e32 v[8:9], v[144:145]
	v_lshl_add_u64 v[14:15], v[58:59], 0, v[22:23]
	v_mov_b64_e32 v[10:11], v[202:203]
	v_mov_b64_e32 v[12:13], v[204:205]
	v_pk_mul_f32 v[2:3], v[2:3], v[62:63]
	v_mov_b64_e32 v[14:15], v[180:181]
	v_mov_b64_e32 v[16:17], v[182:183]
	v_pk_mul_f32 v[4:5], v[4:5], v[62:63]
	v_add_u32_e32 v18, 0x1c04, v75
	v_add_u32_e32 v19, 0x1c0c, v75
	s_waitcnt vmcnt(2)
	v_pk_mul_f32 v[2:3], v[2:3], v[6:7]
	v_pk_mul_f32 v[4:5], v[4:5], v[8:9]
	s_waitcnt vmcnt(1)
	v_pk_add_f32 v[6:7], v[10:11], 1.0 op_sel_hi:[1,0]
	v_pk_add_f32 v[8:9], v[12:13], 1.0 op_sel_hi:[1,0]
	s_waitcnt vmcnt(0)
	v_pk_fma_f32 v[2:3], v[2:3], v[6:7], v[14:15]
	v_pk_fma_f32 v[4:5], v[4:5], v[8:9], v[16:17]
	ds_write2_b32 v18, v2, v3 offset1:1
	ds_write2_b32 v19, v4, v5 offset1:1
	s_and_saveexec_b64 s[0:1], vcc
	s_cbranch_execz .LBB0_1241
	v_mov_b32_e32 v29, v179
	v_cvt_pk_bf16_f32 v2, v2, v3
	v_cvt_pk_bf16_f32 v3, v4, v5
	v_lshl_add_u64 v[4:5], v[56:57], 0, v[28:29]
	global_store_dwordx2 v[4:5], v[2:3], off
	s_branch .LBB0_1241
